# v22 + peeled first K-iteration (no accumulator zeroing) + MLA row-max skip under gain guard + no s_nop 4 in attention DMA blocks + leader publish before invalidate
# speedup vs baseline: 1.0163x; 1.0129x over previous
.LBB0_1478:
	s_add_u32 s26, s0, s24
	s_addc_u32 s27, s53, s25
	s_lshl_b32 s51, s57, 13
	s_add_i32 s58, s51, s43
	s_mov_b32 s59, m0
	s_mov_b32 m0, s58
	s_nop 0
	global_load_lds_dwordx4 v181, s[26:27]
	s_mov_b32 m0, s59
	s_waitcnt lgkmcnt(11)
	v_mfma_f32_32x32x16_bf16 v[66:81], v[82:85], v[98:101], v[50:65]
	s_lshl_b32 s58, s49, 13
	s_waitcnt lgkmcnt(10)
	v_mfma_f32_32x32x16_bf16 v[82:97], v[158:161], v[98:101], v[50:65]
	v_add_u32_e32 v158, s58, v183
	s_waitcnt lgkmcnt(9)
	v_mfma_f32_32x32x16_bf16 v[66:81], v[162:165], v[106:109], v[66:81]
	s_waitcnt lgkmcnt(8)
	v_mfma_f32_32x32x16_bf16 v[82:97], v[150:153], v[106:109], v[82:97]
	s_waitcnt lgkmcnt(7)
	v_mfma_f32_32x32x16_bf16 v[66:81], v[146:149], v[102:105], v[66:81]
	s_waitcnt lgkmcnt(6)
	v_mfma_f32_32x32x16_bf16 v[82:97], v[142:145], v[102:105], v[82:97]
	s_waitcnt lgkmcnt(5)
	v_mfma_f32_32x32x16_bf16 v[66:81], v[138:141], v[114:117], v[66:81]
	ds_read_b64_tr_b16 v[150:151], v158 offset:24576
	ds_read_b64_tr_b16 v[152:153], v158 offset:25088
	ds_read_b64_tr_b16 v[146:147], v158 offset:25600
	ds_read_b64_tr_b16 v[148:149], v158 offset:26112
	ds_read_b64_tr_b16 v[142:143], v158 offset:26624
	ds_read_b64_tr_b16 v[144:145], v158 offset:27136
	ds_read_b64_tr_b16 v[138:139], v158 offset:27648
	ds_read_b64_tr_b16 v[140:141], v158 offset:28160
	s_waitcnt lgkmcnt(12)
	v_mfma_f32_32x32x16_bf16 v[82:97], v[134:137], v[114:117], v[82:97]
	s_waitcnt lgkmcnt(11)
	v_mfma_f32_32x32x16_bf16 v[66:81], v[130:133], v[110:113], v[66:81]
	s_waitcnt lgkmcnt(10)
	v_mfma_f32_32x32x16_bf16 v[82:97], v[126:129], v[110:113], v[82:97]
	s_waitcnt lgkmcnt(9)
	v_mfma_f32_32x32x16_bf16 v[66:81], v[122:125], v[118:121], v[66:81]
	ds_read_b64_tr_b16 v[134:135], v158 offset:28672
	ds_read_b64_tr_b16 v[136:137], v158 offset:29184
	ds_read_b64_tr_b16 v[130:131], v158 offset:29696
	ds_read_b64_tr_b16 v[132:133], v158 offset:30208
	ds_read_b64_tr_b16 v[126:127], v158 offset:30720
	ds_read_b64_tr_b16 v[128:129], v158 offset:31232
	ds_read_b64_tr_b16 v[122:123], v158 offset:31744
	ds_read_b64_tr_b16 v[124:125], v158 offset:32256
	s_waitcnt lgkmcnt(14)
	v_mfma_f32_32x32x16_bf16 v[82:97], v[154:157], v[118:121], v[82:97]
	s_cmp_lg_u32 s101, 0
	s_cbranch_scc1 .Lmla2_fast
	s_nop 1
	v_max_f32_e32 v154, v67, v67
	v_max_f32_e32 v155, v66, v66
	v_max_f32_e32 v154, v155, v154
	s_nop 6
	v_max3_f32 v155, v68, v69, v83
	v_max3_f32 v154, v154, v82, v84
	v_max3_f32 v154, v154, v85, v70
	v_max3_f32 v155, v155, v72, v73
	v_max3_f32 v154, v154, v71, v86
	v_max3_f32 v155, v155, v88, v89
	v_max3_f32 v154, v154, v87, v74
	v_max3_f32 v155, v155, v76, v77
	v_max3_f32 v154, v154, v75, v90
	v_max3_f32 v155, v155, v92, v93
	v_max3_f32 v154, v154, v91, v78
	v_max3_f32 v155, v155, v80, v81
	v_max3_f32 v154, v154, v79, v94
	v_max3_f32 v155, v155, v96, v97
	v_max3_f32 v154, v154, v95, v155
	v_mov_b32_e32 v155, v154
	s_nop 1
	v_permlane32_swap_b32_e32 v154, v155
	v_max_f32_e32 v155, v155, v155
	v_max_f32_e32 v154, v154, v154
	v_max_f32_e32 v154, v154, v155
	v_cmp_lt_f32_e32 vcc, s47, v154
	s_cbranch_vccz .LBB0_1482
	v_max_f32_e32 v50, v154, v154
	v_max_f32_e32 v154, 0, v50
	v_exp_f32_e64 v155, -v154
	v_add_f32_e32 v171, v171, v154
	v_xor_b32_e32 v50, 0x80000000, v171
	v_mov_b32_e32 v51, v50
	v_mov_b32_e32 v52, v50
	v_mov_b32_e32 v53, v50
	v_mov_b32_e32 v54, v50
	v_mov_b32_e32 v55, v50
	v_mov_b32_e32 v56, v50
	v_mov_b32_e32 v57, v50
	v_mov_b32_e32 v58, v50
	v_mov_b32_e32 v59, v50
	v_mov_b32_e32 v60, v50
	v_mov_b32_e32 v61, v50
	v_mov_b32_e32 v62, v50
	v_mov_b32_e32 v63, v50
	v_mov_b32_e32 v64, v50
	v_mov_b32_e32 v65, v50
	s_and_saveexec_b64 s[26:27], s[6:7]
	ds_write_b32 v186, v155 offset:40960
	s_or_b64 exec, exec, s[26:27]
	v_add_u32_e32 v164, s42, v187
	ds_read_b128 v[156:159], v164 offset:41024
	ds_read_b128 v[160:163], v164 offset:41056
	ds_read_b128 v[196:199], v164 offset:40960
	ds_read_b128 v[200:203], v164 offset:40992
	v_pk_add_f32 v[66:67], v[66:67], v[154:155] op_sel_hi:[1,0] neg_lo:[0,1] neg_hi:[0,1]
	v_pk_add_f32 v[82:83], v[82:83], v[154:155] op_sel_hi:[1,0] neg_lo:[0,1] neg_hi:[0,1]
	v_pk_add_f32 v[68:69], v[68:69], v[154:155] op_sel_hi:[1,0] neg_lo:[0,1] neg_hi:[0,1]
	v_pk_add_f32 v[84:85], v[84:85], v[154:155] op_sel_hi:[1,0] neg_lo:[0,1] neg_hi:[0,1]
	v_pk_add_f32 v[70:71], v[70:71], v[154:155] op_sel_hi:[1,0] neg_lo:[0,1] neg_hi:[0,1]
	v_pk_add_f32 v[86:87], v[86:87], v[154:155] op_sel_hi:[1,0] neg_lo:[0,1] neg_hi:[0,1]
	v_pk_add_f32 v[72:73], v[72:73], v[154:155] op_sel_hi:[1,0] neg_lo:[0,1] neg_hi:[0,1]
	v_pk_add_f32 v[88:89], v[88:89], v[154:155] op_sel_hi:[1,0] neg_lo:[0,1] neg_hi:[0,1]
	v_pk_add_f32 v[74:75], v[74:75], v[154:155] op_sel_hi:[1,0] neg_lo:[0,1] neg_hi:[0,1]
	v_pk_add_f32 v[90:91], v[90:91], v[154:155] op_sel_hi:[1,0] neg_lo:[0,1] neg_hi:[0,1]
	v_pk_add_f32 v[76:77], v[76:77], v[154:155] op_sel_hi:[1,0] neg_lo:[0,1] neg_hi:[0,1]
	v_pk_add_f32 v[92:93], v[92:93], v[154:155] op_sel_hi:[1,0] neg_lo:[0,1] neg_hi:[0,1]
	v_pk_add_f32 v[78:79], v[78:79], v[154:155] op_sel_hi:[1,0] neg_lo:[0,1] neg_hi:[0,1]
	v_pk_add_f32 v[94:95], v[94:95], v[154:155] op_sel_hi:[1,0] neg_lo:[0,1] neg_hi:[0,1]
	v_pk_add_f32 v[80:81], v[80:81], v[154:155] op_sel_hi:[1,0] neg_lo:[0,1] neg_hi:[0,1]
	v_pk_add_f32 v[96:97], v[96:97], v[154:155] op_sel_hi:[1,0] neg_lo:[0,1] neg_hi:[0,1]
	v_mul_f32_e32 v173, v173, v155
	s_waitcnt lgkmcnt(2)
	v_pk_mul_f32 v[30:31], v[30:31], v[160:161]
	v_pk_mul_f32 v[26:27], v[26:27], v[156:157]
	s_waitcnt lgkmcnt(0)
	v_pk_mul_f32 v[22:23], v[22:23], v[200:201]
	v_pk_mul_f32 v[32:33], v[32:33], v[162:163]
	v_pk_mul_f32 v[28:29], v[28:29], v[158:159]
	v_pk_mul_f32 v[24:25], v[24:25], v[202:203]
	v_pk_mul_f32 v[20:21], v[20:21], v[198:199]
	v_pk_mul_f32 v[18:19], v[18:19], v[196:197]
	v_pk_mul_f32 v[46:47], v[46:47], v[160:161]
	v_pk_mul_f32 v[42:43], v[42:43], v[156:157]
	v_pk_mul_f32 v[38:39], v[38:39], v[200:201]
	v_pk_mul_f32 v[48:49], v[48:49], v[162:163]
	v_pk_mul_f32 v[44:45], v[44:45], v[158:159]
	v_pk_mul_f32 v[40:41], v[40:41], v[202:203]
	v_pk_mul_f32 v[36:37], v[36:37], v[198:199]
	v_pk_mul_f32 v[34:35], v[34:35], v[196:197]
